# m3 + FFN-down LN normalise: parameter vectors of the next 64-column block prefetched during the current block (was two serial round trips per block)
# speedup vs baseline: 1.0024x; 1.0024x over previous
.LBB0_578:
	v_lshl_add_u32 v188, v200, 3, 0
	s_waitcnt lgkmcnt(0)
	v_cmp_ne_u32_e32 vcc, 0, v162
	ds_read_b64 v[162:163], v188 offset:8192
	s_or_b64 s[40:41], vcc, s[58:59]
	v_add_u32_e32 v174, s24, v200
	s_add_u32 s0, s56, 0x3400000
	v_ashrrev_i32_e32 v175, 31, v174
	s_waitcnt lgkmcnt(0)
	v_sub_f32_e32 v69, v69, v162
	v_sub_f32_e32 v68, v68, v162
	v_sub_f32_e32 v67, v67, v162
	v_sub_f32_e32 v66, v66, v162
	s_addc_u32 s1, s57, 0
	v_lshlrev_b64 v[166:167], 10, v[174:175]
	v_pk_mul_f32 v[66:67], v[162:163], v[66:67] op_sel:[1,0]
	v_pk_mul_f32 v[68:69], v[162:163], v[68:69] op_sel:[1,0]
	s_waitcnt vmcnt(0)
	v_pk_fma_f32 v[162:163], v[130:131], v[66:67], v[134:135]
	v_pk_fma_f32 v[164:165], v[132:133], v[68:69], v[136:137]
	s_and_b64 vcc, exec, s[38:39]
	v_lshl_add_u64 v[176:177], v[166:167], 1, s[0:1]
	global_load_dwordx4 v[226:229], v[178:179], off offset:64
	global_load_dwordx4 v[230:233], v[180:181], off offset:64
	s_cbranch_vccnz .Lpfs0
	v_lshl_add_u64 v[234:235], s[8:9], 0, v[142:143]
	v_lshl_add_u64 v[234:235], v[234:235], 0, s[62:63]
	global_load_dwordx4 v[234:237], v[234:235], off offset:64
	v_lshl_add_u64 v[238:239], s[10:11], 0, v[142:143]
	v_lshl_add_u64 v[238:239], v[238:239], 0, s[62:63]
	global_load_dwordx4 v[238:241], v[238:239], off offset:64
.Lpfs0:
	s_cbranch_vccnz .LBB0_580
	v_pk_fma_f32 v[66:67], v[172:173], v[164:165], v[140:141]
	v_pk_fma_f32 v[68:69], v[170:171], v[162:163], v[138:139]
	s_nop 0
	v_cvt_pk_bf16_f32 v68, v68, v69
	v_cvt_pk_bf16_f32 v66, v66, v67
	s_nop 0
	v_cndmask_b32_e64 v67, v66, v221, s[40:41]
	v_cndmask_b32_e64 v66, v68, v221, s[40:41]
	v_lshl_add_u64 v[68:69], v[160:161], 1, v[176:177]
	global_store_dwordx2 v[68:69], v[66:67], off

.LBB0_594:
	v_mov_b32_e32 v210, 0
	s_and_b64 vcc, exec, s[38:39]
	v_mov_b32_e32 v211, 0
	v_mov_b32_e32 v212, 0
	v_mov_b32_e32 v213, 0
	v_mov_b32_e32 v94, 0
	v_mov_b32_e32 v95, 0
	v_mov_b32_e32 v96, 0
	v_mov_b32_e32 v97, 0
	s_waitcnt vmcnt(0)
	v_mov_b64_e32 v[66:67], v[226:227]
	v_mov_b64_e32 v[68:69], v[228:229]
	v_mov_b64_e32 v[78:79], v[230:231]
	v_mov_b64_e32 v[80:81], v[232:233]
	s_cbranch_vccnz .LBB0_596
	v_pk_add_f32 v[212:213], v[236:237], 1.0 op_sel_hi:[1,0]
	v_pk_add_f32 v[210:211], v[234:235], 1.0 op_sel_hi:[1,0]
	v_mov_b64_e32 v[94:95], v[238:239]
	v_mov_b64_e32 v[96:97], v[240:241]
	s_add_u32 s0, s8, s62
	s_addc_u32 s1, s9, s63
.LBB0_596:
	ds_read_b64 v[134:135], v188 offset:8192
	s_and_b64 vcc, exec, s[38:39]
	s_waitcnt lgkmcnt(0)
	v_sub_f32_e32 v37, v37, v134
	v_sub_f32_e32 v36, v36, v134
	v_sub_f32_e32 v35, v35, v134
	v_sub_f32_e32 v34, v34, v134
	v_pk_mul_f32 v[34:35], v[134:135], v[34:35] op_sel:[1,0]
	v_pk_mul_f32 v[36:37], v[134:135], v[36:37] op_sel:[1,0]
	s_waitcnt vmcnt(0)
	v_pk_fma_f32 v[138:139], v[66:67], v[34:35], v[78:79]
	v_pk_fma_f32 v[134:135], v[68:69], v[36:37], v[80:81]
	global_load_dwordx4 v[226:229], v[178:179], off offset:512
	global_load_dwordx4 v[230:233], v[180:181], off offset:512
	s_cbranch_vccnz .Lpfs1
	v_lshl_add_u64 v[234:235], s[8:9], 0, v[142:143]
	v_lshl_add_u64 v[234:235], v[234:235], 0, s[62:63]
	global_load_dwordx4 v[234:237], v[234:235], off offset:512
	v_lshl_add_u64 v[238:239], s[10:11], 0, v[142:143]
	v_lshl_add_u64 v[238:239], v[238:239], 0, s[62:63]
	global_load_dwordx4 v[238:241], v[238:239], off offset:512
.Lpfs1:
	s_cbranch_vccnz .LBB0_598
	v_pk_fma_f32 v[34:35], v[212:213], v[134:135], v[96:97]
	v_pk_fma_f32 v[36:37], v[210:211], v[138:139], v[94:95]
	s_nop 0
	v_cvt_pk_bf16_f32 v36, v36, v37
	v_cvt_pk_bf16_f32 v34, v34, v35
	s_nop 0
	v_cndmask_b32_e64 v35, v34, v221, s[40:41]
	v_cndmask_b32_e64 v34, v36, v221, s[40:41]
	v_lshl_add_u64 v[36:37], v[160:161], 1, v[176:177]
	global_store_dwordx2 v[36:37], v[34:35], off offset:32

.LBB0_612:
	v_mov_b32_e32 v210, 0
	s_and_b64 vcc, exec, s[38:39]
	v_mov_b32_e32 v211, 0
	v_mov_b32_e32 v212, 0
	v_mov_b32_e32 v213, 0
	v_mov_b32_e32 v62, 0
	v_mov_b32_e32 v63, 0
	v_mov_b32_e32 v64, 0
	v_mov_b32_e32 v65, 0
	s_waitcnt vmcnt(0)
	v_mov_b64_e32 v[34:35], v[226:227]
	v_mov_b64_e32 v[36:37], v[228:229]
	v_mov_b64_e32 v[46:47], v[230:231]
	v_mov_b64_e32 v[48:49], v[232:233]
	s_cbranch_vccnz .LBB0_614
	v_pk_add_f32 v[212:213], v[236:237], 1.0 op_sel_hi:[1,0]
	v_pk_add_f32 v[210:211], v[234:235], 1.0 op_sel_hi:[1,0]
	v_mov_b64_e32 v[62:63], v[238:239]
	v_mov_b64_e32 v[64:65], v[240:241]
	s_add_u32 s0, s8, s62
	s_addc_u32 s1, s9, s63
.LBB0_614:
	ds_read_b64 v[78:79], v188 offset:8192
	s_and_b64 vcc, exec, s[38:39]
	s_waitcnt lgkmcnt(0)
	v_sub_f32_e32 v17, v17, v78
	v_sub_f32_e32 v16, v16, v78
	v_sub_f32_e32 v15, v15, v78
	v_sub_f32_e32 v14, v14, v78
	v_pk_mul_f32 v[14:15], v[78:79], v[14:15] op_sel:[1,0]
	v_pk_mul_f32 v[16:17], v[78:79], v[16:17] op_sel:[1,0]
	s_waitcnt vmcnt(0)
	v_pk_fma_f32 v[90:91], v[34:35], v[14:15], v[46:47]
	v_pk_fma_f32 v[78:79], v[36:37], v[16:17], v[48:49]
	global_load_dwordx4 v[226:229], v[178:179], off offset:576
	global_load_dwordx4 v[230:233], v[180:181], off offset:576
	s_cbranch_vccnz .Lpfs2
	v_lshl_add_u64 v[234:235], s[8:9], 0, v[142:143]
	v_lshl_add_u64 v[234:235], v[234:235], 0, s[62:63]
	global_load_dwordx4 v[234:237], v[234:235], off offset:576
	v_lshl_add_u64 v[238:239], s[10:11], 0, v[142:143]
	v_lshl_add_u64 v[238:239], v[238:239], 0, s[62:63]
	global_load_dwordx4 v[238:241], v[238:239], off offset:576
.Lpfs2:
	s_cbranch_vccnz .LBB0_616
	v_pk_fma_f32 v[14:15], v[212:213], v[78:79], v[64:65]
	v_pk_fma_f32 v[16:17], v[210:211], v[90:91], v[62:63]
	s_nop 0
	v_cvt_pk_bf16_f32 v16, v16, v17
	v_cvt_pk_bf16_f32 v14, v14, v15
	s_nop 0
	v_cndmask_b32_e64 v15, v14, v221, s[40:41]
	v_cndmask_b32_e64 v14, v16, v221, s[40:41]
	v_lshl_add_u64 v[16:17], v[160:161], 1, v[176:177]
	global_store_dwordx2 v[16:17], v[14:15], off offset:256

.LBB0_630:
	v_mov_b32_e32 v62, 0
	s_and_b64 vcc, exec, s[38:39]
	v_mov_b32_e32 v63, 0
	v_mov_b32_e32 v64, 0
	v_mov_b32_e32 v65, 0
	v_mov_b32_e32 v30, 0
	v_mov_b32_e32 v31, 0
	v_mov_b32_e32 v32, 0
	v_mov_b32_e32 v33, 0
	s_waitcnt vmcnt(0)
	v_mov_b64_e32 v[14:15], v[226:227]
	v_mov_b64_e32 v[16:17], v[228:229]
	v_mov_b64_e32 v[22:23], v[230:231]
	v_mov_b64_e32 v[24:25], v[232:233]
	s_cbranch_vccnz .LBB0_632
	v_pk_add_f32 v[64:65], v[236:237], 1.0 op_sel_hi:[1,0]
	v_pk_add_f32 v[62:63], v[234:235], 1.0 op_sel_hi:[1,0]
	v_mov_b64_e32 v[30:31], v[238:239]
	v_mov_b64_e32 v[32:33], v[240:241]
	s_add_u32 s0, s8, s62
	s_addc_u32 s1, s9, s63
